# VH: hoist 6 of 8 V-fragment ds_read_b64_tr above the exp/rcp chain in the unmasked attention tile (on v45)
# speedup vs baseline: 1.0038x; 1.0038x over previous
.LBB0_651:
	s_max_i32 s0, s14, 0
	s_mov_b32 s6, s14
	s_add_i32 s14, s0, -1
	s_lshl_b32 s0, s14, 5
	s_add_i32 s0, s23, s0
	s_cmp_gt_i32 s6, 0
	s_waitcnt vmcnt(0)
	s_cselect_b32 s0, s0, 0x8002
	s_waitcnt lgkmcnt(0)
	v_or_b32_e32 v2, s0, v135
	v_ashrrev_i32_e32 v3, 31, v2
	v_lshlrev_b64 v[2:3], 11, v[2:3]
	ds_write_b128 v167, v[108:111]
	ds_write_b128 v167, v[104:107] offset:144
	ds_write_b128 v167, v[100:103] offset:288
	ds_write_b128 v167, v[96:99] offset:432
	ds_write_b128 v168, v[92:95] offset:4608
	ds_write_b128 v168, v[88:91] offset:4800
	ds_write_b128 v168, v[84:87] offset:4992
	ds_write_b128 v168, v[80:83] offset:5184
	v_lshl_or_b32 v2, v158, 1, v2
	v_lshl_add_u64 v[4:5], s[24:25], 0, v[2:3]
	v_lshl_add_u64 v[2:3], s[26:27], 0, v[2:3]
	global_load_dwordx4 v[108:111], v[4:5], off offset:-4096
	global_load_dwordx4 v[104:107], v[4:5], off offset:-2048
	global_load_dwordx4 v[100:103], v[4:5], off
	global_load_dwordx4 v[96:99], v[4:5], off offset:2048
	global_load_dwordx4 v[92:95], v[2:3], off offset:-4096
	global_load_dwordx4 v[88:91], v[2:3], off offset:-2048
	global_load_dwordx4 v[84:87], v[2:3], off
	global_load_dwordx4 v[80:83], v[2:3], off offset:2048
	ds_read_b128 v[128:131], v169
	ds_read_b128 v[10:13], v169 offset:32
	ds_read_b128 v[6:9], v169 offset:64
	ds_read_b128 v[2:5], v169 offset:96
	s_cmp_lt_i32 s6, 0
	s_cselect_b64 s[0:1], -1, 0
	s_cmp_gt_i32 s6, -1
	s_cselect_b64 s[2:3], -1, 0
	s_cmp_lg_u32 s6, s22
	s_cselect_b64 s[6:7], -1, 0
	s_and_b64 s[6:7], s[2:3], s[6:7]
	s_mov_b64 s[18:19], -1
	s_and_b64 vcc, exec, s[6:7]
	v_mbcnt_hi_u32_b32 v1, -1, v195
	s_mov_b64 s[6:7], -1
	s_cbranch_vccz .LBB0_653
	s_waitcnt lgkmcnt(3)
	v_mfma_f32_32x32x16_bf16 v[48:63], v[128:131], v[112:115], 0
	s_mov_b64 s[6:7], 0
	s_waitcnt lgkmcnt(2)
	v_mfma_f32_32x32x16_bf16 v[48:63], v[10:13], v[116:119], v[48:63]
	s_waitcnt lgkmcnt(1)
	v_mfma_f32_32x32x16_bf16 v[48:63], v[6:9], v[120:123], v[48:63]
	s_waitcnt lgkmcnt(0)
	v_mfma_f32_32x32x16_bf16 v[48:63], v[2:5], v[124:127], v[48:63]
	ds_read_b64_tr_b16 v[188:189], v141 offset:3072
	ds_read_b64_tr_b16 v[190:191], v141 offset:4608
	ds_read_b64_tr_b16 v[196:197], v141 offset:64
	ds_read_b64_tr_b16 v[198:199], v141 offset:1600
	ds_read_b64_tr_b16 v[184:185], v141 offset:3136
	ds_read_b64_tr_b16 v[186:187], v141 offset:4672
	s_nop 11
	v_exp_f32_e32 v14, v48
	v_exp_f32_e32 v15, v49
	v_exp_f32_e32 v48, v50
	v_exp_f32_e32 v49, v51
	v_exp_f32_e32 v50, v52
	v_exp_f32_e32 v51, v53
	v_exp_f32_e32 v52, v54
	v_exp_f32_e32 v53, v55
	v_exp_f32_e32 v54, v56
	v_exp_f32_e32 v55, v57
	v_exp_f32_e32 v56, v58
	v_exp_f32_e32 v57, v59
	v_exp_f32_e32 v58, v60
	v_exp_f32_e32 v59, v61
	v_exp_f32_e32 v60, v62
	v_exp_f32_e32 v61, v63
	v_pk_add_f32 v[14:15], v[14:15], 1.0 op_sel_hi:[1,0]
	v_pk_add_f32 v[48:49], v[48:49], 1.0 op_sel_hi:[1,0]
	v_pk_add_f32 v[58:59], v[58:59], 1.0 op_sel_hi:[1,0]
	v_pk_add_f32 v[50:51], v[50:51], 1.0 op_sel_hi:[1,0]
	v_pk_add_f32 v[52:53], v[52:53], 1.0 op_sel_hi:[1,0]
	v_rcp_f32_e32 v14, v14
	v_rcp_f32_e32 v15, v15
	v_rcp_f32_e32 v48, v48
	v_rcp_f32_e32 v49, v49
	v_rcp_f32_e32 v192, v58
	v_rcp_f32_e32 v193, v59
	v_pk_add_f32 v[58:59], v[60:61], 1.0 op_sel_hi:[1,0]
	v_pk_add_f32 v[54:55], v[54:55], 1.0 op_sel_hi:[1,0]
	v_pk_add_f32 v[56:57], v[56:57], 1.0 op_sel_hi:[1,0]
	v_rcp_f32_e32 v50, v50
	v_rcp_f32_e32 v51, v51
	v_rcp_f32_e32 v52, v52
	v_rcp_f32_e32 v53, v53
	v_rcp_f32_e32 v205, v59
	v_rcp_f32_e32 v68, v54
	v_rcp_f32_e32 v69, v55
	v_rcp_f32_e32 v70, v56
	v_rcp_f32_e32 v71, v57
	v_rcp_f32_e32 v204, v58
	v_pk_add_f32 v[54:55], v[14:15], 1.0 op_sel_hi:[1,0] neg_lo:[1,0] neg_hi:[1,0]
	v_pk_add_f32 v[56:57], v[48:49], 1.0 op_sel_hi:[1,0] neg_lo:[1,0] neg_hi:[1,0]
	v_pk_add_f32 v[62:63], v[50:51], 1.0 op_sel_hi:[1,0] neg_lo:[1,0] neg_hi:[1,0]
	v_pk_add_f32 v[64:65], v[52:53], 1.0 op_sel_hi:[1,0] neg_lo:[1,0] neg_hi:[1,0]
	v_pk_mul_f32 v[58:59], v[54:55], v[56:57]
	v_pk_add_f32 v[72:73], v[68:69], 1.0 op_sel_hi:[1,0] neg_lo:[1,0] neg_hi:[1,0]
	v_pk_add_f32 v[74:75], v[70:71], 1.0 op_sel_hi:[1,0] neg_lo:[1,0] neg_hi:[1,0]
	v_mul_f32_e32 v214, v58, v59
	v_pk_mul_f32 v[58:59], v[62:63], v[64:65]
	v_pk_add_f32 v[206:207], v[192:193], 1.0 op_sel_hi:[1,0] neg_lo:[1,0] neg_hi:[1,0]
	v_pk_add_f32 v[76:77], v[204:205], 1.0 op_sel_hi:[1,0] neg_lo:[1,0] neg_hi:[1,0]
	v_mul_f32_e32 v54, v58, v59
	v_pk_mul_f32 v[58:59], v[72:73], v[74:75]
	v_mov_b32_e32 v67, v54
	v_mul_f32_e32 v62, v58, v59
	v_pk_mul_f32 v[58:59], v[206:207], v[76:77]
	v_mov_b32_e32 v61, v62
	v_mul_f32_e32 v58, v58, v59
	v_mov_b32_e32 v59, v58
	v_mov_b32_e32 v215, v214
	v_permlane32_swap_b32_e32 v67, v54
	v_permlane32_swap_b32_e32 v61, v62
	v_permlane32_swap_b32_e32 v58, v59
	v_permlane32_swap_b32_e32 v214, v215
	s_nop 1
	v_mul_f32_e32 v58, v58, v59
	v_mul_f32_e32 v62, v62, v58
	v_mul_f32_e32 v61, v61, v62
	v_mul_f32_e32 v54, v54, v61
	v_mov_b32_e32 v60, v215
	v_mul_f32_e32 v66, v67, v54
	v_mul_f32_e32 v206, v60, v66
	v_cndmask_b32_e64 v60, v66, v206, s[4:5]
	v_cndmask_b32_e64 v72, 1.0, v59, s[4:5]
	v_mul_f32_e32 v59, v139, v60
	v_cndmask_b32_e64 v54, v61, v54, s[4:5]
	v_cndmask_b32_e64 v61, v58, v62, s[4:5]
	v_mul_f32_e32 v58, v57, v59
	v_mul_f32_e32 v57, v56, v58
	v_mul_f32_e32 v56, v55, v57
	v_mul_f32_e32 v55, v139, v54
	v_mul_f32_e32 v54, v65, v55
	v_pk_mul_f32 v[14:15], v[14:15], v[56:57]
	v_mul_f32_e32 v57, v64, v54
	v_mul_f32_e32 v79, v139, v61
	v_mul_f32_e32 v56, v63, v57
	v_mul_f32_e32 v78, v75, v79
	v_pk_mul_f32 v[48:49], v[48:49], v[58:59]
	v_pk_mul_f32 v[50:51], v[50:51], v[56:57]
	v_pk_mul_f32 v[52:53], v[52:53], v[54:55]
	v_cvt_pk_bf16_f32 v200, v14, v15
	v_mul_f32_e32 v15, v74, v78
	v_mul_f32_e32 v211, v139, v72
	ds_read_b64_tr_b16 v[64:65], v141
	ds_read_b64_tr_b16 v[66:67], v141 offset:1536
	s_waitcnt lgkmcnt(0)
	v_cvt_pk_bf16_f32 v201, v48, v49
	v_cvt_pk_bf16_f32 v202, v50, v51
	v_cvt_pk_bf16_f32 v203, v52, v53
	v_mul_f32_e32 v14, v73, v15
	v_mul_f32_e32 v210, v211, v77
	v_mfma_f32_32x32x16_bf16 v[48:63], v[64:67], v[200:203], v[32:47]
	v_mul_f32_e64 v14, v68, v14
	v_mul_f32_e64 v15, v69, v15
	v_mul_f32_e64 v208, v70, v78
	v_mul_f32_e64 v209, v71, v79
	v_mul_f32_e32 v213, v76, v210
	v_mul_f32_e32 v212, v207, v213
	v_pk_mul_f32 v[192:193], v[192:193], v[212:213]
	v_mfma_f32_32x32x16_bf16 v[64:79], v[196:199], v[200:203], v[16:31]
	v_cvt_pk_bf16_f32 v196, v14, v15
	v_mov_b32_e32 v14, v214
	v_mul_f32_e32 v14, v14, v206
	v_mul_f32_e32 v14, v139, v14
	v_mul_f32_e64 v200, v204, v210
	v_mul_f32_e64 v201, v205, v211
	v_cmp_gt_f32_e32 vcc, s21, v14
	v_cvt_pk_bf16_f32 v197, v208, v209
	v_cvt_pk_bf16_f32 v198, v192, v193
	v_cvt_pk_bf16_f32 v199, v200, v201
	s_cmp_eq_u64 vcc, exec
	s_cselect_b64 s[18:19], -1, 0
	v_mfma_f32_32x32x16_bf16 v[48:63], v[188:191], v[196:199], v[48:63]
	v_mfma_f32_32x32x16_bf16 v[64:79], v[184:187], v[196:199], v[64:79]
